# r53 layout variant: spatial-gating unit code shifted by 4 bytes, later code by 8 (code alignment tuning)
# speedup vs baseline: 1.0090x; 1.0090x over previous
.LBB0_533:
	s_or_b64 exec, exec, s[4:5]
	s_and_b64 exec, exec, s[0:1]
	s_cbranch_execz .LBB0_540
	v_readlane_b32 s0, v253, 17
	s_nop 1
	v_lshl_add_u32 v1, v5, 2, s0
	s_mov_b64 s[0:1], 0
	s_branch .LBB0_536
	s_nop 0
